# PREP0 modgemv: 20 serialized (load, wait, silu, ds_write) iterations unrolled into one batch of 20 loads behind a single wait + previous
# speedup vs baseline: 1.0050x; 1.0009x over previous
.LBB0_58:
	s_and_b64 vcc, exec, s[4:5]
	s_cbranch_vccz .LBB0_23
	v_mov_b32_e32 v72, v164
	v_and_b32_e32 v73, 0xff, v72
	v_lshlrev_b32_e32 v0, 2, v73
	v_add_u32_e32 v4, s23, v0
	v_lshl_add_u64 v[2:3], s[16:17], 0, v[0:1]
	v_lshl_add_u64 v[206:207], s[8:9], 0, v[0:1]
	global_load_dword v180, v[2:3], off
	global_load_dword v181, v[2:3], off offset:1024
	global_load_dword v182, v[2:3], off offset:2048
	global_load_dword v183, v[2:3], off offset:3072
	v_add_co_u32_e32 v208, vcc, 0x1000, v2
	s_nop 1
	v_addc_co_u32_e32 v209, vcc, 0, v3, vcc
	global_load_dword v184, v[208:209], off
	global_load_dword v185, v[208:209], off offset:1024
	global_load_dword v186, v[208:209], off offset:2048
	global_load_dword v187, v[208:209], off offset:3072
	v_add_co_u32_e32 v208, vcc, 0x1000, v208
	s_nop 1
	v_addc_co_u32_e32 v209, vcc, 0, v209, vcc
	global_load_dword v188, v[208:209], off
	global_load_dword v189, v[208:209], off offset:1024
	global_load_dword v190, v[208:209], off offset:2048
	global_load_dword v191, v[208:209], off offset:3072
	v_add_co_u32_e32 v208, vcc, 0x1000, v208
	s_nop 1
	v_addc_co_u32_e32 v209, vcc, 0, v209, vcc
	global_load_dword v192, v[208:209], off
	global_load_dword v193, v[208:209], off offset:1024
	global_load_dword v194, v[208:209], off offset:2048
	global_load_dword v195, v[208:209], off offset:3072
	global_load_dword v196, v[206:207], off
	global_load_dword v197, v[206:207], off offset:1024
	global_load_dword v198, v[206:207], off offset:2048
	global_load_dword v199, v[206:207], off offset:3072
	s_waitcnt vmcnt(0)
	v_mul_f32_e32 v200, 0xbfb8aa3b, v180
	v_exp_f32_e32 v200, v200
	s_nop 0
	v_add_f32_e32 v200, 1.0, v200
	v_div_scale_f32 v201, s[24:25], v200, v200, v180
	v_rcp_f32_e32 v202, v201
	v_div_scale_f32 v203, vcc, v180, v200, v180
	v_fma_f32 v204, -v201, v202, 1.0
	v_fmac_f32_e32 v202, v204, v202
	v_mul_f32_e32 v204, v203, v202
	v_fma_f32 v205, -v201, v204, v203
	v_fmac_f32_e32 v204, v205, v202
	v_fma_f32 v201, -v201, v204, v203
	v_div_fmas_f32 v201, v201, v202, v204
	v_div_fixup_f32 v180, v201, v200, v180
	ds_write_b32 v4, v180
	v_mul_f32_e32 v200, 0xbfb8aa3b, v181
	v_exp_f32_e32 v200, v200
	s_nop 0
	v_add_f32_e32 v200, 1.0, v200
	v_div_scale_f32 v201, s[24:25], v200, v200, v181
	v_rcp_f32_e32 v202, v201
	v_div_scale_f32 v203, vcc, v181, v200, v181
	v_fma_f32 v204, -v201, v202, 1.0
	v_fmac_f32_e32 v202, v204, v202
	v_mul_f32_e32 v204, v203, v202
	v_fma_f32 v205, -v201, v204, v203
	v_fmac_f32_e32 v204, v205, v202
	v_fma_f32 v201, -v201, v204, v203
	v_div_fmas_f32 v201, v201, v202, v204
	v_div_fixup_f32 v181, v201, v200, v181
	ds_write_b32 v4, v181 offset:1024
	v_mul_f32_e32 v200, 0xbfb8aa3b, v182
	v_exp_f32_e32 v200, v200
	s_nop 0
	v_add_f32_e32 v200, 1.0, v200
	v_div_scale_f32 v201, s[24:25], v200, v200, v182
	v_rcp_f32_e32 v202, v201
	v_div_scale_f32 v203, vcc, v182, v200, v182
	v_fma_f32 v204, -v201, v202, 1.0
	v_fmac_f32_e32 v202, v204, v202
	v_mul_f32_e32 v204, v203, v202
	v_fma_f32 v205, -v201, v204, v203
	v_fmac_f32_e32 v204, v205, v202
	v_fma_f32 v201, -v201, v204, v203
	v_div_fmas_f32 v201, v201, v202, v204
	v_div_fixup_f32 v182, v201, v200, v182
	ds_write_b32 v4, v182 offset:2048
	v_mul_f32_e32 v200, 0xbfb8aa3b, v183
	v_exp_f32_e32 v200, v200
	s_nop 0
	v_add_f32_e32 v200, 1.0, v200
	v_div_scale_f32 v201, s[24:25], v200, v200, v183
	v_rcp_f32_e32 v202, v201
	v_div_scale_f32 v203, vcc, v183, v200, v183
	v_fma_f32 v204, -v201, v202, 1.0
	v_fmac_f32_e32 v202, v204, v202
	v_mul_f32_e32 v204, v203, v202
	v_fma_f32 v205, -v201, v204, v203
	v_fmac_f32_e32 v204, v205, v202
	v_fma_f32 v201, -v201, v204, v203
	v_div_fmas_f32 v201, v201, v202, v204
	v_div_fixup_f32 v183, v201, v200, v183
	ds_write_b32 v4, v183 offset:3072
	v_mul_f32_e32 v200, 0xbfb8aa3b, v184
	v_exp_f32_e32 v200, v200
	s_nop 0
	v_add_f32_e32 v200, 1.0, v200
	v_div_scale_f32 v201, s[24:25], v200, v200, v184
	v_rcp_f32_e32 v202, v201
	v_div_scale_f32 v203, vcc, v184, v200, v184
	v_fma_f32 v204, -v201, v202, 1.0
	v_fmac_f32_e32 v202, v204, v202
	v_mul_f32_e32 v204, v203, v202
	v_fma_f32 v205, -v201, v204, v203
	v_fmac_f32_e32 v204, v205, v202
	v_fma_f32 v201, -v201, v204, v203
	v_div_fmas_f32 v201, v201, v202, v204
	v_div_fixup_f32 v184, v201, v200, v184
	ds_write_b32 v4, v184 offset:4096
	v_mul_f32_e32 v200, 0xbfb8aa3b, v185
	v_exp_f32_e32 v200, v200
	s_nop 0
	v_add_f32_e32 v200, 1.0, v200
	v_div_scale_f32 v201, s[24:25], v200, v200, v185
	v_rcp_f32_e32 v202, v201
	v_div_scale_f32 v203, vcc, v185, v200, v185
	v_fma_f32 v204, -v201, v202, 1.0
	v_fmac_f32_e32 v202, v204, v202
	v_mul_f32_e32 v204, v203, v202
	v_fma_f32 v205, -v201, v204, v203
	v_fmac_f32_e32 v204, v205, v202
	v_fma_f32 v201, -v201, v204, v203
	v_div_fmas_f32 v201, v201, v202, v204
	v_div_fixup_f32 v185, v201, v200, v185
	ds_write_b32 v4, v185 offset:5120
	v_mul_f32_e32 v200, 0xbfb8aa3b, v186
	v_exp_f32_e32 v200, v200
	s_nop 0
	v_add_f32_e32 v200, 1.0, v200
	v_div_scale_f32 v201, s[24:25], v200, v200, v186
	v_rcp_f32_e32 v202, v201
	v_div_scale_f32 v203, vcc, v186, v200, v186
	v_fma_f32 v204, -v201, v202, 1.0
	v_fmac_f32_e32 v202, v204, v202
	v_mul_f32_e32 v204, v203, v202
	v_fma_f32 v205, -v201, v204, v203
	v_fmac_f32_e32 v204, v205, v202
	v_fma_f32 v201, -v201, v204, v203
	v_div_fmas_f32 v201, v201, v202, v204
	v_div_fixup_f32 v186, v201, v200, v186
	ds_write_b32 v4, v186 offset:6144
	v_mul_f32_e32 v200, 0xbfb8aa3b, v187
	v_exp_f32_e32 v200, v200
	s_nop 0
	v_add_f32_e32 v200, 1.0, v200
	v_div_scale_f32 v201, s[24:25], v200, v200, v187
	v_rcp_f32_e32 v202, v201
	v_div_scale_f32 v203, vcc, v187, v200, v187
	v_fma_f32 v204, -v201, v202, 1.0
	v_fmac_f32_e32 v202, v204, v202
	v_mul_f32_e32 v204, v203, v202
	v_fma_f32 v205, -v201, v204, v203
	v_fmac_f32_e32 v204, v205, v202
	v_fma_f32 v201, -v201, v204, v203
	v_div_fmas_f32 v201, v201, v202, v204
	v_div_fixup_f32 v187, v201, v200, v187
	ds_write_b32 v4, v187 offset:7168
	v_mul_f32_e32 v200, 0xbfb8aa3b, v188
	v_exp_f32_e32 v200, v200
	s_nop 0
	v_add_f32_e32 v200, 1.0, v200
	v_div_scale_f32 v201, s[24:25], v200, v200, v188
	v_rcp_f32_e32 v202, v201
	v_div_scale_f32 v203, vcc, v188, v200, v188
	v_fma_f32 v204, -v201, v202, 1.0
	v_fmac_f32_e32 v202, v204, v202
	v_mul_f32_e32 v204, v203, v202
	v_fma_f32 v205, -v201, v204, v203
	v_fmac_f32_e32 v204, v205, v202
	v_fma_f32 v201, -v201, v204, v203
	v_div_fmas_f32 v201, v201, v202, v204
	v_div_fixup_f32 v188, v201, v200, v188
	ds_write_b32 v4, v188 offset:8192
	v_mul_f32_e32 v200, 0xbfb8aa3b, v189
	v_exp_f32_e32 v200, v200
	s_nop 0
	v_add_f32_e32 v200, 1.0, v200
	v_div_scale_f32 v201, s[24:25], v200, v200, v189
	v_rcp_f32_e32 v202, v201
	v_div_scale_f32 v203, vcc, v189, v200, v189
	v_fma_f32 v204, -v201, v202, 1.0
	v_fmac_f32_e32 v202, v204, v202
	v_mul_f32_e32 v204, v203, v202
	v_fma_f32 v205, -v201, v204, v203
	v_fmac_f32_e32 v204, v205, v202
	v_fma_f32 v201, -v201, v204, v203
	v_div_fmas_f32 v201, v201, v202, v204
	v_div_fixup_f32 v189, v201, v200, v189
	ds_write_b32 v4, v189 offset:9216
	v_mul_f32_e32 v200, 0xbfb8aa3b, v190
	v_exp_f32_e32 v200, v200
	s_nop 0
	v_add_f32_e32 v200, 1.0, v200
	v_div_scale_f32 v201, s[24:25], v200, v200, v190
	v_rcp_f32_e32 v202, v201
	v_div_scale_f32 v203, vcc, v190, v200, v190
	v_fma_f32 v204, -v201, v202, 1.0
	v_fmac_f32_e32 v202, v204, v202
	v_mul_f32_e32 v204, v203, v202
	v_fma_f32 v205, -v201, v204, v203
	v_fmac_f32_e32 v204, v205, v202
	v_fma_f32 v201, -v201, v204, v203
	v_div_fmas_f32 v201, v201, v202, v204
	v_div_fixup_f32 v190, v201, v200, v190
	ds_write_b32 v4, v190 offset:10240
	v_mul_f32_e32 v200, 0xbfb8aa3b, v191
	v_exp_f32_e32 v200, v200
	s_nop 0
	v_add_f32_e32 v200, 1.0, v200
	v_div_scale_f32 v201, s[24:25], v200, v200, v191
	v_rcp_f32_e32 v202, v201
	v_div_scale_f32 v203, vcc, v191, v200, v191
	v_fma_f32 v204, -v201, v202, 1.0
	v_fmac_f32_e32 v202, v204, v202
	v_mul_f32_e32 v204, v203, v202
	v_fma_f32 v205, -v201, v204, v203
	v_fmac_f32_e32 v204, v205, v202
	v_fma_f32 v201, -v201, v204, v203
	v_div_fmas_f32 v201, v201, v202, v204
	v_div_fixup_f32 v191, v201, v200, v191
	ds_write_b32 v4, v191 offset:11264
	v_mul_f32_e32 v200, 0xbfb8aa3b, v192
	v_exp_f32_e32 v200, v200
	s_nop 0
	v_add_f32_e32 v200, 1.0, v200
	v_div_scale_f32 v201, s[24:25], v200, v200, v192
	v_rcp_f32_e32 v202, v201
	v_div_scale_f32 v203, vcc, v192, v200, v192
	v_fma_f32 v204, -v201, v202, 1.0
	v_fmac_f32_e32 v202, v204, v202
	v_mul_f32_e32 v204, v203, v202
	v_fma_f32 v205, -v201, v204, v203
	v_fmac_f32_e32 v204, v205, v202
	v_fma_f32 v201, -v201, v204, v203
	v_div_fmas_f32 v201, v201, v202, v204
	v_div_fixup_f32 v192, v201, v200, v192
	ds_write_b32 v4, v192 offset:12288
	v_mul_f32_e32 v200, 0xbfb8aa3b, v193
	v_exp_f32_e32 v200, v200
	s_nop 0
	v_add_f32_e32 v200, 1.0, v200
	v_div_scale_f32 v201, s[24:25], v200, v200, v193
	v_rcp_f32_e32 v202, v201
	v_div_scale_f32 v203, vcc, v193, v200, v193
	v_fma_f32 v204, -v201, v202, 1.0
	v_fmac_f32_e32 v202, v204, v202
	v_mul_f32_e32 v204, v203, v202
	v_fma_f32 v205, -v201, v204, v203
	v_fmac_f32_e32 v204, v205, v202
	v_fma_f32 v201, -v201, v204, v203
	v_div_fmas_f32 v201, v201, v202, v204
	v_div_fixup_f32 v193, v201, v200, v193
	ds_write_b32 v4, v193 offset:13312
	v_mul_f32_e32 v200, 0xbfb8aa3b, v194
	v_exp_f32_e32 v200, v200
	s_nop 0
	v_add_f32_e32 v200, 1.0, v200
	v_div_scale_f32 v201, s[24:25], v200, v200, v194
	v_rcp_f32_e32 v202, v201
	v_div_scale_f32 v203, vcc, v194, v200, v194
	v_fma_f32 v204, -v201, v202, 1.0
	v_fmac_f32_e32 v202, v204, v202
	v_mul_f32_e32 v204, v203, v202
	v_fma_f32 v205, -v201, v204, v203
	v_fmac_f32_e32 v204, v205, v202
	v_fma_f32 v201, -v201, v204, v203
	v_div_fmas_f32 v201, v201, v202, v204
	v_div_fixup_f32 v194, v201, v200, v194
	ds_write_b32 v4, v194 offset:14336
	v_mul_f32_e32 v200, 0xbfb8aa3b, v195
	v_exp_f32_e32 v200, v200
	s_nop 0
	v_add_f32_e32 v200, 1.0, v200
	v_div_scale_f32 v201, s[24:25], v200, v200, v195
	v_rcp_f32_e32 v202, v201
	v_div_scale_f32 v203, vcc, v195, v200, v195
	v_fma_f32 v204, -v201, v202, 1.0
	v_fmac_f32_e32 v202, v204, v202
	v_mul_f32_e32 v204, v203, v202
	v_fma_f32 v205, -v201, v204, v203
	v_fmac_f32_e32 v204, v205, v202
	v_fma_f32 v201, -v201, v204, v203
	v_div_fmas_f32 v201, v201, v202, v204
	v_div_fixup_f32 v195, v201, v200, v195
	ds_write_b32 v4, v195 offset:15360
	v_mul_f32_e32 v200, 0xbfb8aa3b, v196
	v_exp_f32_e32 v200, v200
	s_nop 0
	v_add_f32_e32 v200, 1.0, v200
	v_div_scale_f32 v201, s[24:25], v200, v200, v196
	v_rcp_f32_e32 v202, v201
	v_div_scale_f32 v203, vcc, v196, v200, v196
	v_fma_f32 v204, -v201, v202, 1.0
	v_fmac_f32_e32 v202, v204, v202
	v_mul_f32_e32 v204, v203, v202
	v_fma_f32 v205, -v201, v204, v203
	v_fmac_f32_e32 v204, v205, v202
	v_fma_f32 v201, -v201, v204, v203
	v_div_fmas_f32 v201, v201, v202, v204
	v_div_fixup_f32 v196, v201, v200, v196
	ds_write_b32 v4, v196 offset:16384
	v_mul_f32_e32 v200, 0xbfb8aa3b, v197
	v_exp_f32_e32 v200, v200
	s_nop 0
	v_add_f32_e32 v200, 1.0, v200
	v_div_scale_f32 v201, s[24:25], v200, v200, v197
	v_rcp_f32_e32 v202, v201
	v_div_scale_f32 v203, vcc, v197, v200, v197
	v_fma_f32 v204, -v201, v202, 1.0
	v_fmac_f32_e32 v202, v204, v202
	v_mul_f32_e32 v204, v203, v202
	v_fma_f32 v205, -v201, v204, v203
	v_fmac_f32_e32 v204, v205, v202
	v_fma_f32 v201, -v201, v204, v203
	v_div_fmas_f32 v201, v201, v202, v204
	v_div_fixup_f32 v197, v201, v200, v197
	ds_write_b32 v4, v197 offset:17408
	v_mul_f32_e32 v200, 0xbfb8aa3b, v198
	v_exp_f32_e32 v200, v200
	s_nop 0
	v_add_f32_e32 v200, 1.0, v200
	v_div_scale_f32 v201, s[24:25], v200, v200, v198
	v_rcp_f32_e32 v202, v201
	v_div_scale_f32 v203, vcc, v198, v200, v198
	v_fma_f32 v204, -v201, v202, 1.0
	v_fmac_f32_e32 v202, v204, v202
	v_mul_f32_e32 v204, v203, v202
	v_fma_f32 v205, -v201, v204, v203
	v_fmac_f32_e32 v204, v205, v202
	v_fma_f32 v201, -v201, v204, v203
	v_div_fmas_f32 v201, v201, v202, v204
	v_div_fixup_f32 v198, v201, v200, v198
	ds_write_b32 v4, v198 offset:18432
	v_mul_f32_e32 v200, 0xbfb8aa3b, v199
	v_exp_f32_e32 v200, v200
	s_nop 0
	v_add_f32_e32 v200, 1.0, v200
	v_div_scale_f32 v201, s[24:25], v200, v200, v199
	v_rcp_f32_e32 v202, v201
	v_div_scale_f32 v203, vcc, v199, v200, v199
	v_fma_f32 v204, -v201, v202, 1.0
	v_fmac_f32_e32 v202, v204, v202
	v_mul_f32_e32 v204, v203, v202
	v_fma_f32 v205, -v201, v204, v203
	v_fmac_f32_e32 v204, v205, v202
	v_fma_f32 v201, -v201, v204, v203
	v_div_fmas_f32 v201, v201, v202, v204
	v_div_fixup_f32 v199, v201, v200, v199
	ds_write_b32 v4, v199 offset:19456
	s_mul_hi_i32 s4, s27, 0x2aaaaaab
	s_lshr_b32 s5, s4, 31
	s_ashr_i32 s24, s4, 5
	s_add_i32 s24, s24, s5
	s_mul_i32 s4, s24, 0xc0
	v_lshrrev_b32_e32 v74, 6, v73
	s_sub_i32 s4, s27, s4
	v_and_b32_e32 v76, 31, v72
	v_bfe_u32 v77, v73, 5, 1
	v_lshl_or_b32 v2, s4, 5, v76
	v_lshl_or_b32 v34, v74, 8, v77
	v_ashrrev_i32_e32 v3, 31, v2
	v_or_b32_e32 v0, 30, v34
	v_lshlrev_b64 v[6:7], 2, v[2:3]
	v_mul_u32_u24_e32 v0, 0x1800, v0
	v_mad_i64_i32 v[36:37], s[4:5], s24, v70, v[6:7]
	v_lshlrev_b32_e32 v0, 2, v0
	v_lshl_add_u64 v[6:7], v[36:37], 0, v[0:1]
	v_or_b32_e32 v0, 28, v34
	v_mul_u32_u24_e32 v0, 0x1800, v0
	v_lshlrev_b32_e32 v0, 2, v0
	v_lshl_add_u64 v[8:9], v[36:37], 0, v[0:1]
	v_or_b32_e32 v0, 26, v34
	v_mul_u32_u24_e32 v0, 0x1800, v0
	v_lshlrev_b32_e32 v0, 2, v0
	v_lshl_add_u64 v[10:11], v[36:37], 0, v[0:1]
	v_or_b32_e32 v0, 24, v34
	v_mul_u32_u24_e32 v0, 0x1800, v0
	v_lshlrev_b32_e32 v0, 2, v0
	v_lshl_add_u64 v[12:13], v[36:37], 0, v[0:1]
	v_or_b32_e32 v0, 22, v34
	v_mul_u32_u24_e32 v0, 0x1800, v0
	v_lshlrev_b32_e32 v0, 2, v0
	v_lshl_add_u64 v[14:15], v[36:37], 0, v[0:1]
	v_or_b32_e32 v0, 20, v34
	v_mul_u32_u24_e32 v0, 0x1800, v0
	v_lshlrev_b32_e32 v0, 2, v0
	v_lshl_add_u64 v[16:17], v[36:37], 0, v[0:1]
	v_or_b32_e32 v0, 18, v34
	v_mul_u32_u24_e32 v0, 0x1800, v0
	v_lshlrev_b32_e32 v0, 2, v0
	v_lshl_add_u64 v[18:19], v[36:37], 0, v[0:1]
	v_or_b32_e32 v0, 16, v34
	v_mul_u32_u24_e32 v0, 0x1800, v0
	v_lshlrev_b32_e32 v0, 2, v0
	v_lshl_add_u64 v[20:21], v[36:37], 0, v[0:1]
	v_or_b32_e32 v0, 14, v34
	v_mul_u32_u24_e32 v0, 0x1800, v0
	v_lshlrev_b32_e32 v0, 2, v0
	v_lshl_add_u64 v[22:23], v[36:37], 0, v[0:1]
	v_or_b32_e32 v0, 12, v34
	v_mul_u32_u24_e32 v0, 0x1800, v0
	v_lshlrev_b32_e32 v0, 2, v0
	v_lshl_add_u64 v[24:25], v[36:37], 0, v[0:1]
	v_or_b32_e32 v0, 10, v34
	v_mul_u32_u24_e32 v0, 0x1800, v0
	v_lshlrev_b32_e32 v0, 2, v0
	v_lshl_add_u64 v[26:27], v[36:37], 0, v[0:1]
	v_or_b32_e32 v0, 8, v34
	v_mul_u32_u24_e32 v0, 0x1800, v0
	v_lshlrev_b32_e32 v0, 2, v0
	v_lshl_add_u64 v[28:29], v[36:37], 0, v[0:1]
	v_or_b32_e32 v0, 6, v34
	v_mul_u32_u24_e32 v0, 0x1800, v0
	v_lshlrev_b32_e32 v0, 2, v0
	v_lshl_add_u64 v[30:31], v[36:37], 0, v[0:1]
	v_or_b32_e32 v0, 4, v34
	v_mul_u32_u24_e32 v0, 0x1800, v0
	v_lshlrev_b32_e32 v0, 2, v0
	v_lshl_add_u64 v[32:33], v[36:37], 0, v[0:1]
	v_or_b32_e32 v0, 2, v34
	v_mul_u32_u24_e32 v0, 0x1800, v0
	v_lshlrev_b32_e32 v0, 2, v0
	v_lshl_add_u64 v[34:35], v[36:37], 0, v[0:1]
	v_lshlrev_b32_e32 v0, 2, v77
	v_lshl_or_b32 v0, v74, 10, v0
	v_add_u32_e32 v78, s23, v0
	v_mul_u32_u24_e32 v0, 0x180000, v74
	v_mul_u32_u24_e32 v38, 0x1800, v77
	v_or_b32_e32 v0, v0, v38
	v_lshlrev_b32_e32 v0, 2, v0
	v_lshl_add_u64 v[36:37], v[36:37], 0, v[0:1]
	v_mov_b32_e32 v40, 0
	v_lshrrev_b32_e32 v4, 5, v73
	v_lshl_add_u64 v[6:7], s[10:11], 0, v[6:7]
	v_lshl_add_u64 v[8:9], s[10:11], 0, v[8:9]
	v_lshl_add_u64 v[10:11], s[10:11], 0, v[10:11]
	v_lshl_add_u64 v[12:13], s[10:11], 0, v[12:13]
	v_lshl_add_u64 v[14:15], s[10:11], 0, v[14:15]
	v_lshl_add_u64 v[16:17], s[10:11], 0, v[16:17]
	v_lshl_add_u64 v[18:19], s[10:11], 0, v[18:19]
	v_lshl_add_u64 v[20:21], s[10:11], 0, v[20:21]
	v_lshl_add_u64 v[22:23], s[10:11], 0, v[22:23]
	v_lshl_add_u64 v[24:25], s[10:11], 0, v[24:25]
	v_lshl_add_u64 v[26:27], s[10:11], 0, v[26:27]
	v_lshl_add_u64 v[28:29], s[10:11], 0, v[28:29]
	v_lshl_add_u64 v[30:31], s[10:11], 0, v[30:31]
	v_lshl_add_u64 v[32:33], s[10:11], 0, v[32:33]
	v_lshl_add_u64 v[34:35], s[10:11], 0, v[34:35]
	v_lshl_add_u64 v[38:39], s[10:11], 0, v[36:37]
	s_mov_b64 s[4:5], 0
	v_mov_b32_e32 v41, v40
	v_mov_b32_e32 v36, v40
	v_mov_b32_e32 v37, v40
	v_mov_b32_e32 v0, v40
	s_waitcnt lgkmcnt(0)
	s_barrier
